# PV MFMAs reordered ks-major so each packed P quarter is needed later; softmax VALU spread evenly over MFMA gaps by quarter deadlines
# speedup vs baseline: 1.0182x; 1.0050x over previous
; #define LAS __attribute__((address_space(3)))
; #define SBAR() __builtin_amdgcn_sched_barrier(0)
; __device__ __forceinline__ void qkt(f32x16& p0, f32x16& p1, LAS const unsigned char* Ks, const bf16x8* qr, LAS const unsigned char* qt, int r32, int hi) {
;     p0 = (f32x16){}; p1 = (f32x16){};
; #pragma unroll
;     for (int d0 = 0; d0 < 12; ++d0) { const int cb = (d0 * 16 + hi * 8) * 2;
;         const bf16x8 b0 = *(const LAS bf16x8*)(Ks + KSWZ(r32, cb));
;         const bf16x8 b1 = *(const LAS bf16x8*)(Ks + KSWZ(32 + r32, cb));
;         const bf16x8 qf = d0 < QREG ? qr[d0 < QREG ? d0 : 0] : *(const LAS bf16x8*)(qt + (d0 - QREG) * 1024);
;         p0 = __builtin_amdgcn_mfma_f32_32x32x16_bf16(b0, qf, p0, 0, 0, 0);
;         p1 = __builtin_amdgcn_mfma_f32_32x32x16_bf16(b1, qf, p1, 0, 0, 0);
;         if ((d0 & 3) == 3) SBAR(); }
; }
; __device__ __forceinline__ void expP(f32x16& p0, f32x16& p1, float MB) {
; #pragma unroll
;     for (int r = 0; r < 16; ++r) p0[r] = __builtin_amdgcn_exp2f(p0[r] - MB);
; #pragma unroll
;     for (int r = 0; r < 16; ++r) p1[r] = __builtin_amdgcn_exp2f(p1[r] - MB);
; }
; __device__ __forceinline__ void finishP(const f32x16& p0, const f32x16& p1, float& l_reg, bf16x8& pa0, bf16x8& pa1, bf16x8& pa2, bf16x8& pa3) {
;     float ps = 0.f;
; #pragma unroll
;     for (int r = 0; r < 16; ++r) ps += p0[r];
; #pragma unroll
;     for (int r = 0; r < 16; ++r) ps += p1[r];
;     l_reg += ps;
;     ...
;     PK4(p0, 0, pa0); PK4(p0, 8, pa1); PK4(p1, 0, pa2); PK4(p1, 8, pa3);
.LBB0_140:
	s_andn2_b64 vcc, exec, s[50:51]
	s_cbranch_vccnz .LBB0_137
	s_mul_i32 s42, s65, 0x6000
	v_add_u32_e32 v144, s42, v208
	v_add_u32_e32 v213, v144, v209
	v_add_u32_e32 v214, v144, v210
	v_add_u32_e32 v215, v144, v211
	v_add_u32_e32 v220, v144, v212
	ds_read_b128 v[216:219], v213 offset:32768
	ds_read_b128 v[224:227], v214 offset:32768
	ds_read_b128 v[240:243], v215 offset:32768
	ds_read_b128 v[244:247], v220 offset:32768
	v_readfirstlane_b32 s70, v206
	s_nop 3
	s_cmpk_eq_i32 s66, 0x80
	s_cselect_b32 s66, 0x7f800000, s70
	s_waitcnt lgkmcnt(3)
	v_mfma_f32_32x32x16_bf16 v[80:95], v[216:219], v[96:99], 0
	ds_read_b128 v[216:219], v213 offset:32896
	s_waitcnt lgkmcnt(3)
	v_mfma_f32_32x32x16_bf16 v[80:95], v[224:227], v[100:103], v[80:95]
	ds_read_b128 v[224:227], v214 offset:32896
	s_waitcnt lgkmcnt(3)
	v_mfma_f32_32x32x16_bf16 v[80:95], v[240:243], v[104:107], v[80:95]
	ds_read_b128 v[240:243], v215 offset:32896
	s_waitcnt lgkmcnt(3)
	v_mfma_f32_32x32x16_bf16 v[80:95], v[244:247], v[108:111], v[80:95]
	ds_read_b128 v[244:247], v220 offset:32896
	s_waitcnt lgkmcnt(3)
	v_mfma_f32_32x32x16_bf16 v[80:95], v[216:219], v[112:115], v[80:95]
	ds_read_b128 v[216:219], v213 offset:33024
	s_waitcnt lgkmcnt(3)
	v_mfma_f32_32x32x16_bf16 v[80:95], v[224:227], v[116:119], v[80:95]
	ds_read_b128 v[224:227], v214 offset:33024
	s_waitcnt lgkmcnt(3)
	v_mfma_f32_32x32x16_bf16 v[80:95], v[240:243], v[120:123], v[80:95]
	ds_read_b128 v[240:243], v215 offset:33024
	s_waitcnt lgkmcnt(3)
	v_mfma_f32_32x32x16_bf16 v[80:95], v[244:247], v[124:127], v[80:95]
	ds_read_b128 v[244:247], v220 offset:33024
	s_waitcnt lgkmcnt(3)
	v_mfma_f32_32x32x16_bf16 v[80:95], v[216:219], v[128:131], v[80:95]
	ds_read_b128 v[216:219], v213 offset:45056
	s_waitcnt lgkmcnt(3)
	v_mfma_f32_32x32x16_bf16 v[80:95], v[224:227], v[132:135], v[80:95]
	ds_read_b128 v[224:227], v214 offset:45056
	s_waitcnt lgkmcnt(3)
	v_mfma_f32_32x32x16_bf16 v[80:95], v[240:243], v[136:139], v[80:95]
	ds_read_b128 v[240:243], v215 offset:45056
	s_waitcnt lgkmcnt(3)
	v_mfma_f32_32x32x16_bf16 v[80:95], v[244:247], v[140:143], v[80:95]
	ds_read_b128 v[244:247], v220 offset:45056
	s_waitcnt lgkmcnt(3)
	v_mfma_f32_32x32x16_bf16 v[64:79], v[216:219], v[96:99], 0
	ds_read_b128 v[216:219], v213 offset:45184
	s_waitcnt lgkmcnt(3)
	v_mfma_f32_32x32x16_bf16 v[64:79], v[224:227], v[100:103], v[64:79]
	ds_read_b128 v[224:227], v214 offset:45184
	s_waitcnt lgkmcnt(3)
	v_mfma_f32_32x32x16_bf16 v[64:79], v[240:243], v[104:107], v[64:79]
	ds_read_b128 v[240:243], v215 offset:45184
	s_waitcnt lgkmcnt(3)
	v_mfma_f32_32x32x16_bf16 v[64:79], v[244:247], v[108:111], v[64:79]
	ds_read_b128 v[244:247], v220 offset:45184
	s_cmp_eq_u32 s66, 0
	s_cbranch_scc1 .Latt_fast
	v_subrev_f32_e32 v80, s70, v80
	v_subrev_f32_e32 v81, s70, v81
	v_exp_f32_e32 v80, v80
	v_subrev_f32_e32 v82, s70, v82
	v_exp_f32_e32 v81, v81
	s_waitcnt lgkmcnt(3)
	v_mfma_f32_32x32x16_bf16 v[64:79], v[216:219], v[112:115], v[64:79]
	ds_read_b128 v[216:219], v213 offset:45312
	v_subrev_f32_e32 v83, s70, v83
	v_exp_f32_e32 v82, v82
	v_subrev_f32_e32 v84, s70, v84
	v_exp_f32_e32 v83, v83
	v_add_f32_e32 v146, v80, v81
	s_waitcnt lgkmcnt(3)
	v_mfma_f32_32x32x16_bf16 v[64:79], v[224:227], v[116:119], v[64:79]
	ds_read_b128 v[224:227], v214 offset:45312
	v_subrev_f32_e32 v85, s70, v85
	v_exp_f32_e32 v84, v84
	v_add_f32_e32 v146, v82, v146
	v_subrev_f32_e32 v86, s70, v86
	v_exp_f32_e32 v85, v85
	s_waitcnt lgkmcnt(3)
	v_mfma_f32_32x32x16_bf16 v[64:79], v[240:243], v[120:123], v[64:79]
	ds_read_b128 v[240:243], v215 offset:45312
	v_add_f32_e32 v146, v83, v146
	v_subrev_f32_e32 v87, s70, v87
	v_exp_f32_e32 v86, v86
	v_add_f32_e32 v146, v84, v146
	v_exp_f32_e32 v87, v87
	s_waitcnt lgkmcnt(3)
	v_mfma_f32_32x32x16_bf16 v[64:79], v[244:247], v[124:127], v[64:79]
	v_lshl_add_u32 v147, s65, 14, v221
	ds_read_b128 v[244:247], v220 offset:45312
	v_add_f32_e32 v146, v85, v146
	v_add_f32_e32 v146, v86, v146
	v_add_f32_e32 v146, v87, v146
	v_cvt_pk_bf16_f32 v80, v80, v81
	v_cvt_pk_bf16_f32 v81, v82, v83
	s_waitcnt lgkmcnt(3)
	v_mfma_f32_32x32x16_bf16 v[64:79], v[216:219], v[128:131], v[64:79]
	ds_read_b64_tr_b16 v[216:217], v147 offset:0
	ds_read_b64_tr_b16 v[218:219], v147 offset:2048
	v_cvt_pk_bf16_f32 v82, v84, v85
	v_cvt_pk_bf16_f32 v83, v86, v87
	s_waitcnt lgkmcnt(4)
	v_mfma_f32_32x32x16_bf16 v[64:79], v[224:227], v[132:135], v[64:79]
	ds_read_b64_tr_b16 v[224:225], v147 offset:512
	ds_read_b64_tr_b16 v[226:227], v147 offset:2560
	v_permlane32_swap_b32_e32 v80, v82
	v_permlane32_swap_b32_e32 v81, v83
	v_subrev_f32_e32 v88, s66, v88
	v_subrev_f32_e32 v89, s66, v89
	v_exp_f32_e32 v88, v88
	v_subrev_f32_e32 v90, s66, v90
	s_waitcnt lgkmcnt(5)
	v_mfma_f32_32x32x16_bf16 v[64:79], v[240:243], v[136:139], v[64:79]
	ds_read_b64_tr_b16 v[240:241], v147 offset:1024
	ds_read_b64_tr_b16 v[242:243], v147 offset:3072
	v_exp_f32_e32 v89, v89
	v_subrev_f32_e32 v91, s66, v91
	v_exp_f32_e32 v90, v90
	v_add_f32_e32 v146, v88, v146
	v_subrev_f32_e32 v92, s66, v92
	v_exp_f32_e32 v91, v91
	s_waitcnt lgkmcnt(6)
	v_mfma_f32_32x32x16_bf16 v[64:79], v[244:247], v[140:143], v[64:79]
	ds_read_b64_tr_b16 v[244:245], v147 offset:1536
	ds_read_b64_tr_b16 v[246:247], v147 offset:3584
	v_add_f32_e32 v146, v89, v146
	v_subrev_f32_e32 v93, s66, v93
	v_exp_f32_e32 v92, v92
	v_add_f32_e32 v146, v90, v146
	v_subrev_f32_e32 v94, s66, v94
	s_waitcnt lgkmcnt(6)
	v_mfma_f32_32x32x16_bf16 v[48:63], v[80:83], v[216:219], v[48:63]
	ds_read_b64_tr_b16 v[216:217], v147 offset:4096
	ds_read_b64_tr_b16 v[218:219], v147 offset:6144
	v_exp_f32_e32 v93, v93
	v_add_f32_e32 v146, v91, v146
	v_subrev_f32_e32 v95, s66, v95
	v_exp_f32_e32 v94, v94
	v_add_f32_e32 v146, v92, v146
	v_exp_f32_e32 v95, v95
	v_add_f32_e32 v146, v93, v146
	s_waitcnt lgkmcnt(6)
; #define SBAR() __builtin_amdgcn_sched_barrier(0)
; __device__ __forceinline__ void pv_mma(f32x16& od, const VBlk& b, bf16x8 pa0, bf16x8 pa1, bf16x8 pa2, bf16x8 pa3) {
;     ...
;     od = __builtin_amdgcn_mfma_f32_32x32x16_bf16(pa0, PK(b.l0, b.h0), od, 0, 0, 0);
;     od = __builtin_amdgcn_mfma_f32_32x32x16_bf16(pa1, PK(b.l1, b.h1), od, 0, 0, 0);
;     od = __builtin_amdgcn_mfma_f32_32x32x16_bf16(pa2, PK(b.l2, b.h2), od, 0, 0, 0);
;     od = __builtin_amdgcn_mfma_f32_32x32x16_bf16(pa3, PK(b.l3, b.h3), od, 0, 0, 0);
;     ...
; }
; __device__ __forceinline__ void pv_d0(f32x16* o, int vb, bf16x8 pa0, bf16x8 pa1, bf16x8 pa2, bf16x8 pa3) {
;     VBlk A, B;
;     pv_load<0>(A, vb); pv_load<1>(B, vb);
;     asm volatile("s_waitcnt lgkmcnt(8)" ::: "memory"); SBAR(); pv_mma(o[0], A, pa0, pa1, pa2, pa3); SBAR();
;     pv_load<2>(A, vb);
;     asm volatile("s_waitcnt lgkmcnt(8)" ::: "memory"); SBAR(); pv_mma(o[1], B, pa0, pa1, pa2, pa3); SBAR();
;     pv_load<3>(B, vb);
;     asm volatile("s_waitcnt lgkmcnt(8)" ::: "memory"); SBAR(); pv_mma(o[2], A, pa0, pa1, pa2, pa3); SBAR();
;     asm volatile("s_waitcnt lgkmcnt(0)" ::: "memory"); SBAR(); pv_mma(o[3], B, pa0, pa1, pa2, pa3); SBAR();
; }
; __device__ __forceinline__ void finishP(const f32x16& p0, const f32x16& p1, float& l_reg, bf16x8& pa0, bf16x8& pa1, bf16x8& pa2, bf16x8& pa3) {
;     float ps = 0.f;
; #pragma unroll
;     for (int r = 0; r < 16; ++r) ps += p0[r];
; #pragma unroll
;     for (int r = 0; r < 16; ++r) ps += p1[r];
;     l_reg += ps;
;     ...
;     PK4(p0, 0, pa0); PK4(p0, 8, pa1); PK4(p1, 0, pa2); PK4(p1, 8, pa3);
	v_mfma_f32_32x32x16_bf16 v[32:47], v[80:83], v[224:227], v[32:47]
	ds_read_b64_tr_b16 v[224:225], v147 offset:4608
	ds_read_b64_tr_b16 v[226:227], v147 offset:6656
	v_add_f32_e32 v146, v94, v146
	v_add_f32_e32 v146, v95, v146
	v_cvt_pk_bf16_f32 v84, v88, v89
	v_cvt_pk_bf16_f32 v85, v90, v91
	v_cvt_pk_bf16_f32 v86, v92, v93
	v_cvt_pk_bf16_f32 v87, v94, v95
	s_waitcnt lgkmcnt(6)
	v_mfma_f32_32x32x16_bf16 v[16:31], v[80:83], v[240:243], v[16:31]
	ds_read_b64_tr_b16 v[240:241], v147 offset:5120
	ds_read_b64_tr_b16 v[242:243], v147 offset:7168
	v_permlane32_swap_b32_e32 v84, v86
	v_permlane32_swap_b32_e32 v85, v87
	v_subrev_f32_e32 v64, s66, v64
	v_subrev_f32_e32 v65, s66, v65
	v_exp_f32_e32 v64, v64
	v_subrev_f32_e32 v66, s66, v66
	v_exp_f32_e32 v65, v65
	ds_read_b64_tr_b16 v[88:89], v147 offset:5632
	ds_read_b64_tr_b16 v[90:91], v147 offset:7680
	ds_read_b64_tr_b16 v[92:93], v147 offset:8192
	ds_read_b64_tr_b16 v[94:95], v147 offset:10240
	s_waitcnt lgkmcnt(10)
	v_mfma_f32_32x32x16_bf16 v[0:15], v[80:83], v[244:247], v[0:15]
	ds_read_b64_tr_b16 v[244:245], v147 offset:8704
	ds_read_b64_tr_b16 v[246:247], v147 offset:10752
	v_subrev_f32_e32 v67, s66, v67
	v_exp_f32_e32 v66, v66
	v_add_f32_e32 v146, v64, v146
	v_subrev_f32_e32 v68, s66, v68
	v_exp_f32_e32 v67, v67
	v_add_f32_e32 v146, v65, v146
	v_subrev_f32_e32 v69, s66, v69
	s_waitcnt lgkmcnt(10)
	v_mfma_f32_32x32x16_bf16 v[48:63], v[84:87], v[216:219], v[48:63]
	ds_read_b64_tr_b16 v[216:217], v147 offset:9216
	ds_read_b64_tr_b16 v[218:219], v147 offset:11264
	v_exp_f32_e32 v68, v68
	v_add_f32_e32 v146, v66, v146
	v_subrev_f32_e32 v70, s66, v70
	v_exp_f32_e32 v69, v69
	v_add_f32_e32 v146, v67, v146
	v_subrev_f32_e32 v71, s66, v71
	v_exp_f32_e32 v70, v70
	s_waitcnt lgkmcnt(10)
	v_mfma_f32_32x32x16_bf16 v[32:47], v[84:87], v[224:227], v[32:47]
	ds_read_b64_tr_b16 v[224:225], v147 offset:9728
	ds_read_b64_tr_b16 v[226:227], v147 offset:11776
	v_add_f32_e32 v146, v68, v146
	v_exp_f32_e32 v71, v71
	v_add_f32_e32 v146, v69, v146
	v_add_f32_e32 v146, v70, v146
	v_add_f32_e32 v146, v71, v146
	v_cvt_pk_bf16_f32 v64, v64, v65
	v_cvt_pk_bf16_f32 v65, v66, v67
	s_waitcnt lgkmcnt(10)
	v_mfma_f32_32x32x16_bf16 v[16:31], v[84:87], v[240:243], v[16:31]
	ds_read_b64_tr_b16 v[240:241], v147 offset:12288
	ds_read_b64_tr_b16 v[242:243], v147 offset:14336
	v_cvt_pk_bf16_f32 v66, v68, v69
	v_cvt_pk_bf16_f32 v67, v70, v71
	s_waitcnt lgkmcnt(10)
	v_mfma_f32_32x32x16_bf16 v[0:15], v[84:87], v[88:91], v[0:15]
	ds_read_b64_tr_b16 v[88:89], v147 offset:12800
	ds_read_b64_tr_b16 v[90:91], v147 offset:14848
	v_permlane32_swap_b32_e32 v64, v66
	v_permlane32_swap_b32_e32 v65, v67
	v_subrev_f32_e32 v72, s66, v72
	v_subrev_f32_e32 v73, s66, v73
	v_exp_f32_e32 v72, v72
	v_subrev_f32_e32 v74, s66, v74
	v_exp_f32_e32 v73, v73
	v_subrev_f32_e32 v75, s66, v75
	v_exp_f32_e32 v74, v74
	s_waitcnt lgkmcnt(10)
	v_mfma_f32_32x32x16_bf16 v[48:63], v[64:67], v[92:95], v[48:63]
	ds_read_b64_tr_b16 v[92:93], v147 offset:13312
	ds_read_b64_tr_b16 v[94:95], v147 offset:15360
	v_add_f32_e32 v146, v72, v146
	v_subrev_f32_e32 v76, s66, v76
	v_exp_f32_e32 v75, v75
	v_add_f32_e32 v146, v73, v146
	v_subrev_f32_e32 v77, s66, v77
	v_exp_f32_e32 v76, v76
	v_add_f32_e32 v146, v74, v146
	v_subrev_f32_e32 v78, s66, v78
	s_waitcnt lgkmcnt(10)
	v_mfma_f32_32x32x16_bf16 v[32:47], v[64:67], v[244:247], v[32:47]
	ds_read_b64_tr_b16 v[244:245], v147 offset:13824
	ds_read_b64_tr_b16 v[246:247], v147 offset:15872
	v_exp_f32_e32 v77, v77
	v_add_f32_e32 v146, v75, v146
	v_subrev_f32_e32 v79, s66, v79
	v_exp_f32_e32 v78, v78
	v_add_f32_e32 v146, v76, v146
	v_exp_f32_e32 v79, v79
	v_add_f32_e32 v146, v77, v146
	v_add_f32_e32 v146, v78, v146
	s_waitcnt lgkmcnt(10)
	v_mfma_f32_32x32x16_bf16 v[16:31], v[64:67], v[216:219], v[16:31]
	v_add_f32_e32 v146, v79, v146
	v_cvt_pk_bf16_f32 v68, v72, v73
	v_cvt_pk_bf16_f32 v69, v74, v75
	v_cvt_pk_bf16_f32 v70, v76, v77
	v_cvt_pk_bf16_f32 v71, v78, v79
	s_waitcnt lgkmcnt(8)
	v_mfma_f32_32x32x16_bf16 v[0:15], v[64:67], v[224:227], v[0:15]
	v_permlane32_swap_b32_e32 v68, v70
	v_permlane32_swap_b32_e32 v69, v71
	v_add_f32_e32 v155, v155, v146
	s_waitcnt lgkmcnt(6)
	v_mfma_f32_32x32x16_bf16 v[48:63], v[68:71], v[240:243], v[48:63]
	s_waitcnt lgkmcnt(4)
	v_mfma_f32_32x32x16_bf16 v[32:47], v[68:71], v[88:91], v[32:47]
	s_waitcnt lgkmcnt(2)
	v_mfma_f32_32x32x16_bf16 v[16:31], v[68:71], v[92:95], v[16:31]
	s_waitcnt lgkmcnt(0)
	v_mfma_f32_32x32x16_bf16 v[0:15], v[68:71], v[244:247], v[0:15]
	s_branch .LBB0_137
; #define SBAR() __builtin_amdgcn_sched_barrier(0)
; __device__ __forceinline__ void pv_mma(f32x16& od, const VBlk& b, bf16x8 pa0, bf16x8 pa1, bf16x8 pa2, bf16x8 pa3) {
;     ...
;     od = __builtin_amdgcn_mfma_f32_32x32x16_bf16(pa0, PK(b.l0, b.h0), od, 0, 0, 0);
;     od = __builtin_amdgcn_mfma_f32_32x32x16_bf16(pa1, PK(b.l1, b.h1), od, 0, 0, 0);
;     od = __builtin_amdgcn_mfma_f32_32x32x16_bf16(pa2, PK(b.l2, b.h2), od, 0, 0, 0);
;     od = __builtin_amdgcn_mfma_f32_32x32x16_bf16(pa3, PK(b.l3, b.h3), od, 0, 0, 0);
;     ...
; }
; __device__ __forceinline__ void pv_d0(f32x16* o, int vb, bf16x8 pa0, bf16x8 pa1, bf16x8 pa2, bf16x8 pa3) {
;     VBlk A, B;
;     pv_load<0>(A, vb); pv_load<1>(B, vb);
;     asm volatile("s_waitcnt lgkmcnt(8)" ::: "memory"); SBAR(); pv_mma(o[0], A, pa0, pa1, pa2, pa3); SBAR();
;     pv_load<2>(A, vb);
;     asm volatile("s_waitcnt lgkmcnt(8)" ::: "memory"); SBAR(); pv_mma(o[1], B, pa0, pa1, pa2, pa3); SBAR();
;     pv_load<3>(B, vb);
;     asm volatile("s_waitcnt lgkmcnt(8)" ::: "memory"); SBAR(); pv_mma(o[2], A, pa0, pa1, pa2, pa3); SBAR();
;     asm volatile("s_waitcnt lgkmcnt(0)" ::: "memory"); SBAR(); pv_mma(o[3], B, pa0, pa1, pa2, pa3); SBAR();
; }
; __device__ __forceinline__ void expP(f32x16& p0, f32x16& p1, float MB) {
; #pragma unroll
;     for (int r = 0; r < 16; ++r) p0[r] = __builtin_amdgcn_exp2f(p0[r] - MB);
; #pragma unroll
;     for (int r = 0; r < 16; ++r) p1[r] = __builtin_amdgcn_exp2f(p1[r] - MB);
; }
; __device__ __forceinline__ void maskLast(f32x16& p0, f32x16& p1) {
; #pragma unroll
;     for (int r = 8; r < 16; ++r) p0[r] = 0.f;
; #pragma unroll
;     for (int r = 0; r < 16; ++r) p1[r] = 0.f;
; }
; __device__ __forceinline__ void finishP(const f32x16& p0, const f32x16& p1, float& l_reg, bf16x8& pa0, bf16x8& pa1, bf16x8& pa2, bf16x8& pa3) {
;     float ps = 0.f;
; #pragma unroll
;     for (int r = 0; r < 16; ++r) ps += p0[r];
; #pragma unroll
;     for (int r = 0; r < 16; ++r) ps += p1[r];
;     l_reg += ps;
;     ...
;     PK4(p0, 0, pa0); PK4(p0, 8, pa1); PK4(p1, 0, pa2); PK4(p1, 8, pa3);
;     ...
; }
.Latt_fast:
	v_exp_f32_e32 v80, v80
	v_exp_f32_e32 v81, v81
	v_exp_f32_e32 v82, v82
	v_exp_f32_e32 v83, v83
	s_waitcnt lgkmcnt(3)
	v_mfma_f32_32x32x16_bf16 v[64:79], v[216:219], v[112:115], v[64:79]
	ds_read_b128 v[216:219], v213 offset:45312
	v_add_f32_e32 v146, v80, v81
	v_exp_f32_e32 v84, v84
	v_add_f32_e32 v146, v82, v146
	v_exp_f32_e32 v85, v85
	s_waitcnt lgkmcnt(3)
	v_mfma_f32_32x32x16_bf16 v[64:79], v[224:227], v[116:119], v[64:79]
	ds_read_b128 v[224:227], v214 offset:45312
	v_add_f32_e32 v146, v83, v146
	v_exp_f32_e32 v86, v86
	v_add_f32_e32 v146, v84, v146
	v_exp_f32_e32 v87, v87
	s_waitcnt lgkmcnt(3)
	v_mfma_f32_32x32x16_bf16 v[64:79], v[240:243], v[120:123], v[64:79]
	ds_read_b128 v[240:243], v215 offset:45312
	v_add_f32_e32 v146, v85, v146
	v_add_f32_e32 v146, v86, v146
	v_add_f32_e32 v146, v87, v146
	v_cvt_pk_bf16_f32 v80, v80, v81
	s_waitcnt lgkmcnt(3)
	v_mfma_f32_32x32x16_bf16 v[64:79], v[244:247], v[124:127], v[64:79]
	v_lshl_add_u32 v147, s65, 14, v221
	ds_read_b128 v[244:247], v220 offset:45312
	v_cvt_pk_bf16_f32 v81, v82, v83
	v_cvt_pk_bf16_f32 v82, v84, v85
	v_cvt_pk_bf16_f32 v83, v86, v87
	s_waitcnt lgkmcnt(3)
	v_mfma_f32_32x32x16_bf16 v[64:79], v[216:219], v[128:131], v[64:79]
	ds_read_b64_tr_b16 v[216:217], v147 offset:0
	ds_read_b64_tr_b16 v[218:219], v147 offset:2048
	v_permlane32_swap_b32_e32 v80, v82
	v_permlane32_swap_b32_e32 v81, v83
	v_exp_f32_e32 v88, v88
	v_exp_f32_e32 v89, v89
	s_waitcnt lgkmcnt(4)
	v_mfma_f32_32x32x16_bf16 v[64:79], v[224:227], v[132:135], v[64:79]
	ds_read_b64_tr_b16 v[224:225], v147 offset:512
	ds_read_b64_tr_b16 v[226:227], v147 offset:2560
	v_exp_f32_e32 v90, v90
	v_add_f32_e32 v146, v88, v146
	v_exp_f32_e32 v91, v91
	v_add_f32_e32 v146, v89, v146
	s_waitcnt lgkmcnt(5)
	v_mfma_f32_32x32x16_bf16 v[64:79], v[240:243], v[136:139], v[64:79]
	ds_read_b64_tr_b16 v[240:241], v147 offset:1024
	ds_read_b64_tr_b16 v[242:243], v147 offset:3072
	v_exp_f32_e32 v92, v92
	v_add_f32_e32 v146, v90, v146
	v_exp_f32_e32 v93, v93
	v_add_f32_e32 v146, v91, v146
	s_waitcnt lgkmcnt(6)
	v_mfma_f32_32x32x16_bf16 v[64:79], v[244:247], v[140:143], v[64:79]
	ds_read_b64_tr_b16 v[244:245], v147 offset:1536
	ds_read_b64_tr_b16 v[246:247], v147 offset:3584
	v_exp_f32_e32 v94, v94
	v_add_f32_e32 v146, v92, v146
	v_exp_f32_e32 v95, v95
	s_waitcnt lgkmcnt(6)
	v_mfma_f32_32x32x16_bf16 v[48:63], v[80:83], v[216:219], v[48:63]
	ds_read_b64_tr_b16 v[216:217], v147 offset:4096
	ds_read_b64_tr_b16 v[218:219], v147 offset:6144
	v_add_f32_e32 v146, v93, v146
	v_add_f32_e32 v146, v94, v146
	v_add_f32_e32 v146, v95, v146
	v_cvt_pk_bf16_f32 v84, v88, v89
	v_cvt_pk_bf16_f32 v85, v90, v91
	s_waitcnt lgkmcnt(6)
	v_mfma_f32_32x32x16_bf16 v[32:47], v[80:83], v[224:227], v[32:47]
	ds_read_b64_tr_b16 v[224:225], v147 offset:4608
	ds_read_b64_tr_b16 v[226:227], v147 offset:6656
	v_cvt_pk_bf16_f32 v86, v92, v93
	v_cvt_pk_bf16_f32 v87, v94, v95
	s_waitcnt lgkmcnt(6)
	v_mfma_f32_32x32x16_bf16 v[16:31], v[80:83], v[240:243], v[16:31]
	ds_read_b64_tr_b16 v[240:241], v147 offset:5120
	ds_read_b64_tr_b16 v[242:243], v147 offset:7168
	v_permlane32_swap_b32_e32 v84, v86
	v_permlane32_swap_b32_e32 v85, v87
	v_exp_f32_e32 v64, v64
	v_exp_f32_e32 v65, v65
	v_exp_f32_e32 v66, v66
	v_add_f32_e32 v146, v64, v146
	ds_read_b64_tr_b16 v[88:89], v147 offset:5632
	ds_read_b64_tr_b16 v[90:91], v147 offset:7680
	ds_read_b64_tr_b16 v[92:93], v147 offset:8192
	ds_read_b64_tr_b16 v[94:95], v147 offset:10240
	s_waitcnt lgkmcnt(10)
	v_mfma_f32_32x32x16_bf16 v[0:15], v[80:83], v[244:247], v[0:15]
	ds_read_b64_tr_b16 v[244:245], v147 offset:8704
	ds_read_b64_tr_b16 v[246:247], v147 offset:10752
	v_exp_f32_e32 v67, v67
	v_add_f32_e32 v146, v65, v146
	v_exp_f32_e32 v68, v68
	v_add_f32_e32 v146, v66, v146
	v_exp_f32_e32 v69, v69
	v_add_f32_e32 v146, v67, v146
	s_waitcnt lgkmcnt(10)
	v_mfma_f32_32x32x16_bf16 v[48:63], v[84:87], v[216:219], v[48:63]
	ds_read_b64_tr_b16 v[216:217], v147 offset:9216
	ds_read_b64_tr_b16 v[218:219], v147 offset:11264
	v_exp_f32_e32 v70, v70
	v_add_f32_e32 v146, v68, v146
	v_exp_f32_e32 v71, v71
	v_add_f32_e32 v146, v69, v146
	v_add_f32_e32 v146, v70, v146
	s_waitcnt lgkmcnt(10)
	v_mfma_f32_32x32x16_bf16 v[32:47], v[84:87], v[224:227], v[32:47]
	ds_read_b64_tr_b16 v[224:225], v147 offset:9728
	ds_read_b64_tr_b16 v[226:227], v147 offset:11776
	v_add_f32_e32 v146, v71, v146
	v_cvt_pk_bf16_f32 v64, v64, v65
	v_cvt_pk_bf16_f32 v65, v66, v67
	v_cvt_pk_bf16_f32 v66, v68, v69
	v_cvt_pk_bf16_f32 v67, v70, v71
	s_waitcnt lgkmcnt(10)
	v_mfma_f32_32x32x16_bf16 v[16:31], v[84:87], v[240:243], v[16:31]
	ds_read_b64_tr_b16 v[240:241], v147 offset:12288
	ds_read_b64_tr_b16 v[242:243], v147 offset:14336
	v_permlane32_swap_b32_e32 v64, v66
	v_permlane32_swap_b32_e32 v65, v67
	v_exp_f32_e32 v72, v72
	v_exp_f32_e32 v73, v73
	v_exp_f32_e32 v74, v74
	s_waitcnt lgkmcnt(10)
	v_mfma_f32_32x32x16_bf16 v[0:15], v[84:87], v[88:91], v[0:15]
	ds_read_b64_tr_b16 v[88:89], v147 offset:12800
	ds_read_b64_tr_b16 v[90:91], v147 offset:14848
	v_add_f32_e32 v146, v72, v146
	v_exp_f32_e32 v75, v75
	v_add_f32_e32 v146, v73, v146
	v_exp_f32_e32 v76, v76
	v_add_f32_e32 v146, v74, v146
	s_waitcnt lgkmcnt(10)
	v_mfma_f32_32x32x16_bf16 v[48:63], v[64:67], v[92:95], v[48:63]
	ds_read_b64_tr_b16 v[92:93], v147 offset:13312
	ds_read_b64_tr_b16 v[94:95], v147 offset:15360
	v_exp_f32_e32 v77, v77
	v_add_f32_e32 v146, v75, v146
	v_exp_f32_e32 v78, v78
	v_add_f32_e32 v146, v76, v146
	v_exp_f32_e32 v79, v79
	s_waitcnt lgkmcnt(10)
	v_mfma_f32_32x32x16_bf16 v[32:47], v[64:67], v[244:247], v[32:47]
	ds_read_b64_tr_b16 v[244:245], v147 offset:13824
	ds_read_b64_tr_b16 v[246:247], v147 offset:15872
	v_add_f32_e32 v146, v77, v146
	v_add_f32_e32 v146, v78, v146
	v_add_f32_e32 v146, v79, v146
	v_cvt_pk_bf16_f32 v68, v72, v73
	v_cvt_pk_bf16_f32 v69, v74, v75
	s_waitcnt lgkmcnt(10)
	v_mfma_f32_32x32x16_bf16 v[16:31], v[64:67], v[216:219], v[16:31]
	v_cvt_pk_bf16_f32 v70, v76, v77
	v_cvt_pk_bf16_f32 v71, v78, v79
	s_waitcnt lgkmcnt(8)
	v_mfma_f32_32x32x16_bf16 v[0:15], v[64:67], v[224:227], v[0:15]
	v_permlane32_swap_b32_e32 v68, v70
	v_permlane32_swap_b32_e32 v69, v71
	v_add_f32_e32 v155, v155, v146
	s_waitcnt lgkmcnt(6)
	v_mfma_f32_32x32x16_bf16 v[48:63], v[68:71], v[240:243], v[48:63]
	s_waitcnt lgkmcnt(4)
	v_mfma_f32_32x32x16_bf16 v[32:47], v[68:71], v[88:91], v[32:47]
	s_waitcnt lgkmcnt(2)
	v_mfma_f32_32x32x16_bf16 v[16:31], v[68:71], v[92:95], v[16:31]
	s_waitcnt lgkmcnt(0)
	v_mfma_f32_32x32x16_bf16 v[0:15], v[68:71], v[244:247], v[0:15]
	s_branch .LBB0_137
